# half-K-tile stagger between odd and even row-block workgroups at the entry of all six GEMM phases (block index from v244 lane 0)
# baseline (speedup 1.0000x reference)
; #define PG8_STAGE(bufoff, gbase, voff) do { _Pragma("unroll") for (int _i = 0; _i < 2; ++_i) \
;         __builtin_amdgcn_global_load_lds((const unsigned*)((const char*)(gbase) + (voff)[_i]), (PG8_LAS unsigned*)(lds + (bufoff) + ldsw + _i * 8192), 16, 0, 0); } while (0)
; #define PG8_WAIT_V(n) asm volatile("s_waitcnt vmcnt(" #n ")" ::: "memory")
; #define PG8_BAR __builtin_amdgcn_s_barrier()
; template <class Epi, class Sched, bool ALIGN_EPI = false, bool SP2 = false>
; __device__ __forceinline__ void gemm_phase(PG8_LAS unsigned char* lds, const Gemm g, const Sched& S, const Epi& E, const int wid) {
;     ...
;     const char* cA = (const char*)g.A + (size_t)cur.pm * tstep; const char* cB = (const char*)g.Bt + (size_t)cur.pn * tstep;
;     S.a_ready(cur);
;     if constexpr (SP2) {
;         PG8_STAGE(PG8_SB(0, 0), cB, voffB); PG8_STAGE(PG8_SB(0, 1), cB + hstep, voffB); PG8_STAGE(PG8_SA(0, 0), cA, voffA); PG8_STAGE(PG8_SA(0, 1), cA + hstep, voffA);
;         if (wr == 1) PG8_BAR;
;         PG8_WAIT_V(2); PG8_BAR;
.LBB0_141:
	v_readlane_b32 s99, v244, 0
	s_bitcmp1_b32 s99, 3
	s_cbranch_scc0 .Lgst141
	s_sleep 27
